# ssd_scan: y tiles computed transposed, 2 dwordx2 stores per lane and chunk instead of 8 short stores
# baseline (speedup 1.0000x reference)
; DI bf16_t f2bf(float f) { return (bf16_t)(pk2(f, 0.f) & 0xffffu); }
; DI void unpack8(const u32x4& w, float* f) { f[0] = bflo(w.x); f[1] = bfhi(w.x); f[2] = bflo(w.y); f[3] = bfhi(w.y); f[4] = bflo(w.z); f[5] = bfhi(w.z); f[6] = bflo(w.w); f[7] = bfhi(w.w); }
; #define MFMA16(a, b, c) __builtin_amdgcn_mfma_f32_16x16x32_bf16((a), (b), (c), 0, 0, 0)
; DI void ssd_scan(const Params& P, LAS unsigned char* lds) {
;     ...
;             float cum = dtv * a;
; #pragma unroll
;             for (int of = 1; of < 64; of <<= 1) { const float o = __shfl_up(cum, of); if (lane >= of) cum += o; }
;             const float cl = __shfl(cum, 63); const float wend = __expf(cl - cum) * dtv;
;             { const int p8 = wid * 8; const bf16_t* e = (const bf16_t*)&xw;
; #pragma unroll
;               for (int j = 0; j < 8; ++j) Xt[(p8 + j) * 72 + lane] = e[j]; }
; #pragma unroll
;             for (int i = 0; i < 2; ++i) { const int n8 = (wid + 8 * i) * 8; float f[8]; unpack8(bw[i], f);
; #pragma unroll
;                 for (int j = 0; j < 8; ++j) BWt[(n8 + j) * 72 + lane] = f2bf(f[j] * wend); }
;             float cumt[4];
; #pragma unroll
;             for (int j = 0; j < 4; ++j) cumt[j] = __shfl(cum, 16 * mb + 4 * fq + j);
; #pragma unroll
;             for (int i = 0; i < 2; ++i) { const int nb = 2 * hb + i; f32x4 sc = {0.f, 0.f, 0.f, 0.f};
; #pragma unroll
;                 for (int ks = 0; ks < 4; ++ks) sc = MFMA16(ca[ks], bbf[i][ks], sc);
;                 const int s = 16 * nb + fr; const float cums = __shfl(cum, s), dts = __shfl(dtv, s);
; #pragma unroll
;                 for (int j = 0; j < 4; ++j) { const int t = 16 * mb + 4 * fq + j; Pm[t * 72 + s] = f2bf(s <= t ? sc[j] * __expf(cumt[j] - cums) * dts : 0.f); } }
.LBB0_181:
	s_waitcnt vmcnt(2)
	v_mul_f32_e64 v78, v113, -v166
	ds_bpermute_b32 v79, v130, v78
	s_waitcnt vmcnt(9)
	v_mov_b64_e32 v[92:93], v[32:33]
	v_mov_b64_e32 v[90:91], v[30:31]
	s_and_b32 s17, s19, 1
	s_mul_i32 s23, s17, 0xd400
	s_waitcnt lgkmcnt(0)
	v_fma_f32 v79, v113, -v166, v79
	v_cndmask_b32_e64 v94, v79, v78, s[38:39]
	ds_bpermute_b32 v95, v131, v94
	s_waitcnt vmcnt(8)
	v_mov_b64_e32 v[80:81], v[18:19]
	v_mov_b64_e32 v[78:79], v[16:17]
	v_mov_b64_e32 v[88:89], v[28:29]
	v_mov_b64_e32 v[84:85], v[22:23]
	s_waitcnt lgkmcnt(0)
	v_add_f32_e32 v16, v94, v95
	v_cndmask_b32_e64 v16, v16, v94, s[40:41]
	ds_bpermute_b32 v17, v132, v16
	v_lshlrev_b32_e32 v18, 16, v74
	s_add_i32 s25, s23, 0
	v_mov_b64_e32 v[86:87], v[26:27]
	v_mov_b64_e32 v[82:83], v[20:21]
	s_waitcnt lgkmcnt(0)
	v_add_f32_e32 v17, v16, v17
	v_cndmask_b32_e64 v16, v17, v16, s[42:43]
	ds_bpermute_b32 v17, v133, v16
	v_and_b32_e32 v19, 0xffff0000, v74
	v_lshlrev_b32_e32 v20, 16, v75
	v_lshl_add_u32 v28, v120, 1, s25
	v_add_u32_e32 v29, s3, v28
	s_waitcnt lgkmcnt(0)
	v_add_f32_e32 v17, v16, v17
	v_cndmask_b32_e64 v16, v17, v16, s[44:45]
	ds_bpermute_b32 v17, v134, v16
	v_and_b32_e32 v21, 0xffff0000, v75
	ds_write_b16 v29, v70 offset:9216
	ds_write_b16_d16_hi v29, v70 offset:9360
	ds_write_b16 v29, v71 offset:9504
	ds_write_b16_d16_hi v29, v71 offset:9648
	ds_write_b16 v29, v72 offset:9792
	ds_write_b16_d16_hi v29, v72 offset:9936
	ds_write_b16 v29, v73 offset:10080
	ds_write_b16_d16_hi v29, v73 offset:10224
	s_waitcnt lgkmcnt(8)
	v_add_f32_e32 v17, v16, v17
	v_cndmask_b32_e64 v16, v17, v16, s[46:47]
	ds_bpermute_b32 v17, v135, v16
	v_lshlrev_b32_e32 v22, 16, v76
	v_and_b32_e32 v23, 0xffff0000, v76
	v_lshlrev_b32_e32 v26, 16, v77
	v_and_b32_e32 v27, 0xffff0000, v77
	s_waitcnt lgkmcnt(0)
	v_add_f32_e32 v17, v16, v17
	v_cndmask_b32_e64 v30, v17, v16, s[48:49]
	v_and_b32_e32 v215, 15, v187
	v_lshrrev_b32_e32 v216, 4, v187
	v_lshlrev_b32_e32 v217, 2, v216
	v_sub_u32_e32 v217, v215, v217
	v_lshl_add_u32 v218, v217, 2, v136
	ds_bpermute_b32 v219, v218, v30
	ds_bpermute_b32 v170, v123, v30
	ds_bpermute_b32 v174, v136, v30
	ds_bpermute_b32 v173, v137, v30
	ds_bpermute_b32 v172, v138, v30
	ds_bpermute_b32 v171, v139, v30
	s_waitcnt lgkmcnt(4)
	v_sub_f32_e32 v16, v170, v30
	v_mul_f32_e32 v16, 0x3fb8aa3b, v16
	v_exp_f32_e32 v16, v16
	s_xor_b32 s17, s17, 1
	v_add_u32_e32 v118, s18, v169
	v_mov_b64_e32 v[176:177], s[6:7]
	v_mul_f32_e32 v16, v113, v16
	v_mul_f32_e32 v17, v16, v18
	v_mul_f32_e32 v18, v16, v19
	v_mul_f32_e32 v19, v16, v20
	v_cvt_pk_bf16_f32 v17, v17, s0
	v_cvt_pk_bf16_f32 v18, v18, s0
	ds_write_b16 v29, v17 offset:35840
	ds_write_b16 v29, v18 offset:35984
	v_cvt_pk_bf16_f32 v17, v19, s0
	ds_write_b16 v29, v17 offset:36128
	v_mul_f32_e32 v17, v16, v21
	v_cvt_pk_bf16_f32 v17, v17, s0
	ds_write_b16 v29, v17 offset:36272
	v_mul_f32_e32 v17, v16, v22
	v_cvt_pk_bf16_f32 v17, v17, s0
	ds_write_b16 v29, v17 offset:36416
	v_mul_f32_e32 v17, v16, v23
	v_cvt_pk_bf16_f32 v17, v17, s0
	ds_write_b16 v29, v17 offset:36560
	v_mul_f32_e32 v17, v16, v26
	v_cvt_pk_bf16_f32 v17, v17, s0
	ds_write_b16 v29, v17 offset:36704
	v_mul_f32_e32 v17, v16, v27
	v_cvt_pk_bf16_f32 v17, v17, s0
	ds_write_b16 v29, v17 offset:36848
	v_lshlrev_b32_e32 v17, 16, v50
	v_mul_f32_e32 v17, v16, v17
	v_and_b32_e32 v18, 0xffff0000, v50
	v_cvt_pk_bf16_f32 v17, v17, s0
	v_add_u32_e32 v27, s21, v28
	ds_write_b16 v27, v17 offset:35840
	v_mul_f32_e32 v17, v16, v18
	v_lshlrev_b32_e32 v19, 16, v51
	v_cvt_pk_bf16_f32 v17, v17, s0
	ds_write_b16 v29, v17 offset:45200
	v_mul_f32_e32 v17, v16, v19
	v_and_b32_e32 v20, 0xffff0000, v51
	v_cvt_pk_bf16_f32 v17, v17, s0
	ds_write_b16 v29, v17 offset:45344
	v_mul_f32_e32 v17, v16, v20
	v_lshlrev_b32_e32 v21, 16, v52
	v_cvt_pk_bf16_f32 v17, v17, s0
	ds_write_b16 v29, v17 offset:45488
	v_mul_f32_e32 v17, v16, v21
	v_and_b32_e32 v22, 0xffff0000, v52
	v_cvt_pk_bf16_f32 v17, v17, s0
	ds_write_b16 v29, v17 offset:45632
	v_mul_f32_e32 v17, v16, v22
	v_lshlrev_b32_e32 v23, 16, v53
	v_cvt_pk_bf16_f32 v17, v17, s0
	v_and_b32_e32 v26, 0xffff0000, v53
	ds_write_b16 v29, v17 offset:45776
	v_mul_f32_e32 v17, v16, v23
	v_cvt_pk_bf16_f32 v17, v17, s0
	v_mul_f32_e32 v16, v16, v26
	ds_write_b16 v29, v17 offset:45920
	v_cvt_pk_bf16_f32 v20, v16, s0
	s_waitcnt vmcnt(5)
	v_mfma_f32_16x16x32_bf16 v[16:19], v[90:93], v[54:57], 0
	ds_write_b16 v29, v20 offset:46064
	ds_bpermute_b32 v20, v140, v30
	ds_bpermute_b32 v26, v140, v113
	v_mfma_f32_16x16x32_bf16 v[16:19], v[86:89], v[58:61], v[16:19]
	v_add3_u32 v27, s25, v102, v141
	s_mul_i32 s23, s17, 0xd400
	s_waitcnt lgkmcnt(1)
	v_sub_f32_e32 v21, v174, v20
	v_mfma_f32_16x16x32_bf16 v[16:19], v[82:85], v[66:69], v[16:19]
	v_mul_f32_e32 v21, 0x3fb8aa3b, v21
	v_exp_f32_e32 v21, v21
	s_mov_b32 s17, s37
	s_waitcnt vmcnt(4)
	v_mfma_f32_16x16x32_bf16 v[16:19], v[78:81], v[62:65], v[16:19]
	v_add_u32_e32 v175, s25, v24
	v_add_u32_e32 v58, v175, v146
	v_add3_u32 v214, s25, v126, v148
	v_ashrrev_i32_e32 v119, 31, v118
	s_add_i32 s19, s19, 1
	s_nop 2
	v_mul_f32_e32 v16, v16, v21
	v_sub_f32_e32 v21, v173, v20
	v_mul_f32_e32 v21, 0x3fb8aa3b, v21
	v_exp_f32_e32 v21, v21
	s_waitcnt lgkmcnt(0)
	v_mul_f32_e32 v16, v16, v26
	v_cvt_pk_bf16_f32 v16, v16, s0
	v_cndmask_b32_e64 v16, v16, 0, s[50:51]
	ds_write_b16 v27, v16
	v_mul_f32_e32 v16, v17, v21
	v_sub_f32_e32 v17, v172, v20
	v_mul_f32_e32 v17, 0x3fb8aa3b, v17
	v_exp_f32_e32 v17, v17
	v_mul_f32_e32 v16, v16, v26
	v_cvt_pk_bf16_f32 v16, v16, s0
	v_cndmask_b32_e64 v16, v16, 0, s[52:53]
	ds_write_b16 v27, v16 offset:144
	v_mul_f32_e32 v16, v18, v17
	v_sub_f32_e32 v17, v171, v20
	v_mul_f32_e32 v17, 0x3fb8aa3b, v17
	v_exp_f32_e32 v17, v17
	v_mul_f32_e32 v16, v16, v26
	v_cvt_pk_bf16_f32 v16, v16, s0
	s_waitcnt vmcnt(1)
; DI void ssd_scan(const Params& P, LAS unsigned char* lds) {
;     ...
;         SSD_LOAD(b * 2048, dtv, ca);
;         for (int n = 0; n < 32; ++n) {
;             const int row0 = b * 2048 + 64 * n;
;             LAS unsigned char* sb_ = lds + (n & 1) * SSET; LAS unsigned char* so_ = lds + ((n & 1) ^ 1) * SSET;
;             LAS bf16_t* Pm = (LAS bf16_t*)sb_; LAS bf16_t* Xt = (LAS bf16_t*)(sb_ + 9216); LAS bf16_t* Sb = (LAS bf16_t*)(sb_ + 18432); LAS bf16_t* BWt = (LAS bf16_t*)(sb_ + 35840);
;             LAS bf16_t* Sbn = (LAS bf16_t*)(so_ + 18432);
;             float cum = dtv * a;
; #pragma unroll
;             for (int of = 1; of < 64; of <<= 1) { const float o = __shfl_up(cum, of); if (lane >= of) cum += o; }
;             const float cl = __shfl(cum, 63); const float wend = __expf(cl - cum) * dtv;
;             { const int p8 = wid * 8; const bf16_t* e = (const bf16_t*)&xw;
; #pragma unroll
;               for (int j = 0; j < 8; ++j) Xt[(p8 + j) * 72 + lane] = e[j]; }
; #pragma unroll
;             for (int i = 0; i < 2; ++i) { const int n8 = (wid + 8 * i) * 8; float f[8]; unpack8(bw[i], f);
; #pragma unroll
;                 for (int j = 0; j < 8; ++j) BWt[(n8 + j) * 72 + lane] = f2bf(f[j] * wend); }
;             float cumt[4];
; #pragma unroll
;             for (int j = 0; j < 4; ++j) cumt[j] = __shfl(cum, 16 * mb + 4 * fq + j);
; #pragma unroll
;             for (int i = 0; i < 2; ++i) { const int nb = 2 * hb + i; f32x4 sc = {0.f, 0.f, 0.f, 0.f};
; #pragma unroll
;                 for (int ks = 0; ks < 4; ++ks) sc = MFMA16(ca[ks], bbf[i][ks], sc);
;                 const int s = 16 * nb + fr; const float cums = __shfl(cum, s), dts = __shfl(dtv, s);
; #pragma unroll
;                 for (int j = 0; j < 4; ++j) { const int t = 16 * mb + 4 * fq + j; Pm[t * 72 + s] = f2bf(s <= t ? sc[j] * __expf(cumt[j] - cums) * dts : 0.f); } }
;             LDS_BARRIER();
;             float dtn = dtv; bf16x8 cn[4];
; #pragma unroll
;             for (int ks = 0; ks < 4; ++ks) cn[ks] = ca[ks];
;             if (n + 1 < 32) SSD_LOAD(row0 + 64, dtn, cn);
;             f32x4 yi[2], ye[2];
; #pragma unroll
;             for (int i = 0; i < 2; ++i) { yi[i] = (f32x4){0.f, 0.f, 0.f, 0.f}; ye[i] = (f32x4){0.f, 0.f, 0.f, 0.f}; }
; #pragma unroll
;             for (int k2 = 0; k2 < 2; ++k2) { const bf16x8 am = *(const LAS bf16x8*)(Pm + (16 * mb + fr) * 72 + 32 * k2 + 8 * fq);
	v_mfma_f32_16x16x32_bf16 v[20:23], v[90:93], v[46:49], 0
	v_cndmask_b32_e64 v16, v16, 0, s[54:55]
	ds_write_b16 v27, v16 offset:288
	v_mul_f32_e32 v16, v19, v17
	v_mul_f32_e32 v16, v16, v26
	v_cvt_pk_bf16_f32 v26, v16, s0
	v_mfma_f32_16x16x32_bf16 v[16:19], v[86:89], v[38:41], v[20:23]
	v_add_u32_e32 v46, v175, v125
	s_nop 1
	ds_bpermute_b32 v20, v145, v30
	v_mfma_f32_16x16x32_bf16 v[16:19], v[82:85], v[42:45], v[16:19]
	v_cndmask_b32_e64 v21, v26, 0, s[56:57]
	ds_write_b16 v27, v21 offset:432
	ds_bpermute_b32 v21, v145, v113
	s_waitcnt lgkmcnt(2)
	v_sub_f32_e32 v22, v174, v20
	v_mul_f32_e32 v22, 0x3fb8aa3b, v22
	v_exp_f32_e32 v22, v22
	s_waitcnt vmcnt(0)
	v_mfma_f32_16x16x32_bf16 v[16:19], v[78:81], v[34:37], v[16:19]
	v_add_u32_e32 v113, s18, v165
	v_add_u32_e32 v38, 64, v113
	v_mad_i64_i32 v[42:43], s[66:67], v38, s87, v[176:177]
	v_lshl_add_u64 v[42:43], v[42:43], 0, s[16:17]
	s_nop 3
	v_mul_f32_e32 v16, v16, v22
	v_sub_f32_e32 v22, v173, v20
	v_mul_f32_e32 v22, 0x3fb8aa3b, v22
	v_exp_f32_e32 v22, v22
	s_waitcnt lgkmcnt(0)
	v_mul_f32_e32 v16, v16, v21
	v_cvt_pk_bf16_f32 v16, v16, s0
	v_cndmask_b32_e64 v16, v16, 0, s[58:59]
	ds_write_b16 v27, v16 offset:32
	v_mul_f32_e32 v16, v17, v22
	v_sub_f32_e32 v17, v172, v20
	v_mul_f32_e32 v17, 0x3fb8aa3b, v17
	v_exp_f32_e32 v17, v17
	v_mul_f32_e32 v16, v16, v21
	v_cvt_pk_bf16_f32 v16, v16, s0
	v_cndmask_b32_e64 v16, v16, 0, s[60:61]
	ds_write_b16 v27, v16 offset:176
	v_mul_f32_e32 v16, v18, v17
	v_sub_f32_e32 v17, v171, v20
	v_mul_f32_e32 v17, 0x3fb8aa3b, v17
	v_exp_f32_e32 v17, v17
	v_mul_f32_e32 v16, v16, v21
	v_cvt_pk_bf16_f32 v16, v16, s0
	v_cndmask_b32_e64 v16, v16, 0, s[62:63]
	ds_write_b16 v27, v16 offset:320
	v_mul_f32_e32 v16, v19, v17
	v_mul_f32_e32 v16, v16, v21
	v_cvt_pk_bf16_f32 v16, v16, s0
	v_cndmask_b32_e64 v16, v16, 0, s[64:65]
	ds_write_b16 v27, v16 offset:464
	v_mad_i64_i32 v[16:17], s[66:67], v118, s87, v[176:177]
	v_lshl_add_u64 v[18:19], v[16:17], 0, s[36:37]
	v_lshl_add_u64 v[16:17], v[16:17], 0, s[16:17]
	s_waitcnt lgkmcnt(0)
	s_barrier
	v_lshl_add_u64 v[18:19], v[18:19], 0, s[12:13]
	v_lshl_add_u64 v[16:17], v[16:17], 0, s[12:13]
	global_load_dwordx4 v[70:73], v[18:19], off
	v_lshl_add_u64 v[18:19], v[16:17], 0, s[70:71]
	v_add_co_u32_e32 v16, vcc, s86, v16
	v_lshl_add_u64 v[54:55], v[42:43], 0, v[24:25]
	s_nop 0
	v_addc_co_u32_e32 v17, vcc, 0, v17, vcc
	global_load_dwordx4 v[74:77], v[16:17], off
	global_load_dwordx4 v[50:53], v[18:19], off offset:128
	v_add_u32_e32 v16, s18, v168
	v_mad_i64_i32 v[16:17], s[66:67], v16, s87, v[176:177]
	v_lshl_add_u64 v[16:17], v[16:17], 0, s[16:17]
	v_lshl_add_u64 v[16:17], v[16:17], 0, v[24:25]
	v_lshl_add_u64 v[18:19], v[16:17], 0, s[96:97]
	v_add_co_u32_e32 v16, vcc, s86, v16
	v_lshl_add_u64 v[178:179], v[54:55], 0, s[70:71]
	s_nop 0
	v_addc_co_u32_e32 v17, vcc, 0, v17, vcc
	global_load_dwordx4 v[30:33], v[16:17], off offset:1024
	global_load_dwordx4 v[26:29], v[18:19], off offset:64
	global_load_dwordx4 v[20:23], v[18:19], off offset:128
	s_nop 0
	global_load_dwordx4 v[16:19], v[18:19], off offset:192
	ds_read_b128 v[34:37], v46
	ds_read_b128 v[38:41], v58 offset:9216
	ds_read_b128 v[42:45], v58 offset:11520
	ds_read_b128 v[62:65], v58 offset:11584
	ds_read_b128 v[46:49], v46 offset:64
	s_waitcnt lgkmcnt(3)
	v_mfma_f32_16x16x32_bf16 v[38:41], v[38:41], v[34:37], 0
	v_add_co_u32_e32 v54, vcc, s86, v54
	v_lshlrev_b64 v[118:119], 7, v[118:119]
	s_waitcnt lgkmcnt(2)
	v_mfma_f32_16x16x32_bf16 v[34:37], v[42:45], v[34:37], 0
	ds_read_b128 v[42:45], v58 offset:9280
	v_addc_co_u32_e32 v55, vcc, 0, v55, vcc
	s_waitcnt lgkmcnt(0)
	v_mfma_f32_16x16x32_bf16 v[98:101], v[42:45], v[46:49], v[38:41]
	v_add_u32_e32 v42, 0x50, v113
	s_nop 1
	ds_read_b128 v[38:41], v214 offset:18432
	v_mad_i64_i32 v[42:43], s[66:67], v42, s87, v[176:177]
	global_load_dwordx4 v[54:57], v[54:55], off
	v_mfma_f32_16x16x32_bf16 v[94:97], v[62:65], v[46:49], v[34:37]
	global_load_dwordx4 v[58:61], v[178:179], off offset:64
	global_load_dwordx4 v[66:69], v[178:179], off offset:128
	global_load_dwordx4 v[62:65], v[178:179], off offset:192
	v_lshl_add_u64 v[46:47], v[42:43], 0, s[16:17]
	s_waitcnt lgkmcnt(0)
	v_mfma_f32_16x16x32_bf16 v[34:37], v[38:41], v[90:93], 0
	ds_read_b128 v[38:41], v214 offset:22784
	ds_read_b128 v[42:45], v214 offset:18496
	v_lshl_add_u64 v[118:119], s[14:15], 0, v[118:119]
	s_waitcnt lgkmcnt(1)
	v_mfma_f32_16x16x32_bf16 v[38:41], v[38:41], v[90:93], 0
	v_lshl_add_u64 v[90:91], v[46:47], 0, v[24:25]
	ds_read_b128 v[46:49], v214 offset:22848
	v_add_co_u32_e32 v180, vcc, s86, v90
	s_waitcnt lgkmcnt(1)
	v_mfma_f32_16x16x32_bf16 v[34:37], v[42:45], v[86:89], v[34:37]
	ds_read_b128 v[42:45], v214 offset:18560
	v_lshl_add_u64 v[212:213], v[90:91], 0, s[70:71]
	v_addc_co_u32_e32 v181, vcc, 0, v91, vcc
	s_waitcnt lgkmcnt(1)
	v_mfma_f32_16x16x32_bf16 v[86:89], v[46:49], v[86:89], v[38:41]
	ds_read_b128 v[90:93], v214 offset:22912
	global_load_dwordx4 v[46:49], v[180:181], off
	s_nop 0
	global_load_dwordx4 v[38:41], v[212:213], off offset:64
	ds_read_b128 v[180:183], v214 offset:18624
	s_waitcnt lgkmcnt(2)
	v_mfma_f32_16x16x32_bf16 v[176:179], v[42:45], v[82:85], v[34:37]
	global_load_dwordx4 v[42:45], v[212:213], off offset:128
	s_nop 1
	global_load_dwordx4 v[34:37], v[212:213], off offset:192
	global_load_dword v113, v[118:119], off
	s_waitcnt lgkmcnt(1)
	v_mfma_f32_16x16x32_bf16 v[82:85], v[90:93], v[82:85], v[86:89]
	s_nop 2
	ds_read_b128 v[86:89], v214 offset:22976
	s_waitcnt lgkmcnt(1)
	v_mfma_f32_16x16x32_bf16 v[90:93], v[180:183], v[78:81], v[176:179]
	s_waitcnt lgkmcnt(0)
; #define LAS __attribute__((address_space(3)))
; DI unsigned pk2(float lo, float hi) { const f32x2v v = {lo, hi}; const bf16x2v b = __builtin_convertvector(v, bf16x2v); return __builtin_bit_cast(unsigned, b); }
; DI float bf2f(bf16_t b) { return __uint_as_float(((unsigned)b) << 16); }
; DI bf16_t f2bf(float f) { return (bf16_t)(pk2(f, 0.f) & 0xffffu); }
; #define MFMA16(a, b, c) __builtin_amdgcn_mfma_f32_16x16x32_bf16((a), (b), (c), 0, 0, 0)
; DI void ssd_scan(const Params& P, LAS unsigned char* lds) {
;     ...
; #pragma unroll
;             for (int j = 0; j < 4; ++j) { const int tl = 16 * mb + 4 * fq + j, row = row0 + tl; const float ec = __expf(cumt[j]);
; #pragma unroll
;                 for (int i = 0; i < 2; ++i) { const int p = 16 * (2 * hb + i) + fr; const float xv = bf2f(Xt[p * 72 + tl]);
;                     YB[(size_t)row * 2048 + h * 64 + p] = f2bf(yi[i][j] + ec * ye[i][j] + dsk * xv); } }
;             { const float ecl = __expf(cl);
; #pragma unroll
;               for (int i = 0; i < 4; ++i) Sacc[i] *= ecl; }
; #pragma unroll
;             for (int k2 = 0; k2 < 2; ++k2) { const bf16x8 am = *(const LAS bf16x8*)(BWt + (16 * wid + fr) * 72 + 32 * k2 + 8 * fq);
; #pragma unroll
;                 for (int i = 0; i < 4; ++i) { const bf16x8 bb = *(const LAS bf16x8*)(Xt + (16 * i + fr) * 72 + 32 * k2 + 8 * fq); Sacc[i] = MFMA16(am, bb, Sacc[i]); } }
; #pragma unroll
;             for (int i = 0; i < 4; ++i) { u32x2 w; w.x = pk2(Sacc[i][0], Sacc[i][1]); w.y = pk2(Sacc[i][2], Sacc[i][3]); *(LAS u32x2*)(Sbn + (16 * i + fr) * 136 + 16 * wid + 4 * fq) = w; }
;             dtv = dtn;
; #pragma unroll
;             for (int ks = 0; ks < 4; ++ks) ca[ks] = cn[ks];
	v_mfma_f32_16x16x32_bf16 v[78:81], v[86:89], v[78:81], v[82:85]
	v_mul_f32_e32 v220, 0x3fb8aa3b, v219
	v_exp_f32_e32 v220, v220
	v_lshlrev_b32_e32 v222, 1, v124
	v_add3_u32 v222, s25, v222, v146
	v_mul_i32_i24_e32 v221, 0xffffff72, v217
	v_add_u32_e32 v221, v222, v221
	ds_read_u16 v223, v221 offset:9216
	ds_read_u16 v224, v221 offset:9360
	ds_read_u16 v225, v221 offset:9504
	ds_read_u16 v226, v221 offset:9648
	ds_read_u16 v248, v221 offset:11520
	ds_read_u16 v249, v221 offset:11664
	ds_read_u16 v250, v221 offset:11808
	ds_read_u16 v251, v221 offset:11952
	v_add_u32_e32 v228, s18, v109
	v_add_u32_e32 v228, v228, v217
	v_ashrrev_i32_e32 v229, 31, v228
	v_lshlrev_b64 v[228:229], 12, v[228:229]
	v_lshlrev_b32_e32 v230, 1, v217
	v_sub_u32_e32 v230, 0, v230
	v_ashrrev_i32_e32 v231, 31, v230
	v_lshl_add_u64 v[228:229], v[228:229], 0, v[230:231]
	v_lshl_add_u64 v[232:233], v[114:115], 0, v[228:229]
	v_lshl_add_u64 v[234:235], v[116:117], 0, v[228:229]
	s_add_i32 s18, s18, 64
	s_cmpk_eq_i32 s18, 0x7c0
	v_fma_f32 v240, v220, v90, v98
	v_fma_f32 v241, v220, v91, v99
	v_fma_f32 v242, v220, v92, v100
	v_fma_f32 v243, v220, v93, v101
	v_fma_f32 v244, v220, v78, v94
	v_fma_f32 v245, v220, v79, v95
	v_fma_f32 v246, v220, v80, v96
	v_fma_f32 v247, v220, v81, v97
	s_waitcnt lgkmcnt(0)
	v_lshlrev_b32_e32 v223, 16, v223
	v_lshlrev_b32_e32 v224, 16, v224
	v_lshlrev_b32_e32 v225, 16, v225
	v_lshlrev_b32_e32 v226, 16, v226
	v_lshlrev_b32_e32 v248, 16, v248
	v_lshlrev_b32_e32 v249, 16, v249
	v_lshlrev_b32_e32 v250, 16, v250
	v_lshlrev_b32_e32 v251, 16, v251
	v_fmac_f32_e32 v240, v111, v223
	v_fmac_f32_e32 v241, v111, v224
	v_fmac_f32_e32 v242, v111, v225
	v_fmac_f32_e32 v243, v111, v226
	v_fmac_f32_e32 v244, v111, v248
	v_fmac_f32_e32 v245, v111, v249
	v_fmac_f32_e32 v246, v111, v250
	v_fmac_f32_e32 v247, v111, v251
	v_cvt_pk_bf16_f32 v236, v240, v241
	v_cvt_pk_bf16_f32 v237, v242, v243
	v_cvt_pk_bf16_f32 v238, v244, v245
	v_cvt_pk_bf16_f32 v239, v246, v247
	global_store_dwordx2 v[232:233], v[236:237], off
	global_store_dwordx2 v[234:235], v[238:239], off
	v_add_u32_e32 v96, v175, v127
	ds_read_b128 v[84:87], v96 offset:35840
	s_nop 0
	s_nop 0
	v_mul_f32_e32 v80, 0x3fb8aa3b, v170
	v_add_u32_e32 v119, v175, v149
	v_exp_f32_e32 v80, v80
	ds_read_b128 v[88:91], v119 offset:9216
	ds_read_b128 v[92:95], v119 offset:11520
	s_nop 0
	v_pk_mul_f32 v[2:3], v[2:3], v[80:81] op_sel_hi:[1,0]
	v_pk_mul_f32 v[0:1], v[0:1], v[80:81] op_sel_hi:[1,0]
	v_pk_mul_f32 v[6:7], v[6:7], v[80:81] op_sel_hi:[1,0]
	v_pk_mul_f32 v[4:5], v[4:5], v[80:81] op_sel_hi:[1,0]
	s_waitcnt lgkmcnt(1)
	v_mfma_f32_16x16x32_bf16 v[0:3], v[84:87], v[88:91], v[0:3]
	ds_read_b128 v[88:91], v119 offset:13824
	v_pk_mul_f32 v[14:15], v[14:15], v[80:81] op_sel_hi:[1,0]
	v_pk_mul_f32 v[12:13], v[12:13], v[80:81] op_sel_hi:[1,0]
	s_waitcnt lgkmcnt(1)
	v_mfma_f32_16x16x32_bf16 v[4:7], v[84:87], v[92:95], v[4:7]
	ds_read_b128 v[92:95], v119 offset:16128
	ds_read_b128 v[98:101], v96 offset:35904
	s_nop 0
	v_pk_mul_f32 v[10:11], v[10:11], v[80:81] op_sel_hi:[1,0]
	s_waitcnt lgkmcnt(2)
	v_mfma_f32_16x16x32_bf16 v[12:15], v[84:87], v[88:91], v[12:15]
	ds_read_b128 v[88:91], v119 offset:9280
	v_pk_mul_f32 v[8:9], v[8:9], v[80:81] op_sel_hi:[1,0]
	s_nop 0
	s_waitcnt lgkmcnt(2)
	v_mfma_f32_16x16x32_bf16 v[8:11], v[84:87], v[92:95], v[8:11]
	s_nop 0
	s_nop 0
	ds_read_b128 v[84:87], v119 offset:11584
	s_waitcnt lgkmcnt(1)
	v_mfma_f32_16x16x32_bf16 v[0:3], v[98:101], v[88:91], v[0:3]
	s_nop 0
	s_nop 0
	ds_read_b128 v[88:91], v119 offset:13888
	s_nop 0
	ds_read_b128 v[78:81], v119 offset:16192
	s_waitcnt lgkmcnt(2)
	v_mfma_f32_16x16x32_bf16 v[4:7], v[98:101], v[84:87], v[4:7]
	s_nop 0
	s_nop 0
	s_nop 0
	s_waitcnt lgkmcnt(1)
	v_mfma_f32_16x16x32_bf16 v[12:15], v[98:101], v[88:91], v[12:15]
	s_waitcnt lgkmcnt(0)
	v_mfma_f32_16x16x32_bf16 v[8:11], v[98:101], v[78:81], v[8:11]
	v_cvt_pk_bf16_f32 v78, v0, v1
	v_cvt_pk_bf16_f32 v79, v2, v3
	v_add3_u32 v80, v154, s23, v150
	ds_write_b64 v80, v[78:79] offset:18432
	v_cvt_pk_bf16_f32 v78, v4, v5
	v_cvt_pk_bf16_f32 v79, v6, v7
	ds_write_b64 v80, v[78:79] offset:22784
	v_cvt_pk_bf16_f32 v78, v12, v13
	v_cvt_pk_bf16_f32 v79, v14, v15
	ds_write_b64 v80, v[78:79] offset:27136
	v_cvt_pk_bf16_f32 v78, v8, v9
	v_cvt_pk_bf16_f32 v79, v10, v11
	ds_write_b64 v80, v[78:79] offset:31488
	s_cbranch_scc0 .LBB0_181
; DI bf16_t f2bf(float f) { return (bf16_t)(pk2(f, 0.f) & 0xffffu); }
; DI void unpack8(const u32x4& w, float* f) { f[0] = bflo(w.x); f[1] = bfhi(w.x); f[2] = bflo(w.y); f[3] = bfhi(w.y); f[4] = bflo(w.z); f[5] = bfhi(w.z); f[6] = bflo(w.w); f[7] = bfhi(w.w); }
; #define LDS_BARRIER() do { asm volatile("s_waitcnt lgkmcnt(0)" ::: "memory"); __builtin_amdgcn_s_barrier(); asm volatile("" ::: "memory"); } while (0)
; #define MFMA16(a, b, c) __builtin_amdgcn_mfma_f32_16x16x32_bf16((a), (b), (c), 0, 0, 0)
; DI void ssd_scan(const Params& P, LAS unsigned char* lds) {
;     ...
;             float cum = dtv * a;
; #pragma unroll
;             for (int of = 1; of < 64; of <<= 1) { const float o = __shfl_up(cum, of); if (lane >= of) cum += o; }
;             const float cl = __shfl(cum, 63); const float wend = __expf(cl - cum) * dtv;
;             { const int p8 = wid * 8; const bf16_t* e = (const bf16_t*)&xw;
; #pragma unroll
;               for (int j = 0; j < 8; ++j) Xt[(p8 + j) * 72 + lane] = e[j]; }
; #pragma unroll
;             for (int i = 0; i < 2; ++i) { const int n8 = (wid + 8 * i) * 8; float f[8]; unpack8(bw[i], f);
; #pragma unroll
;                 for (int j = 0; j < 8; ++j) BWt[(n8 + j) * 72 + lane] = f2bf(f[j] * wend); }
;             float cumt[4];
; #pragma unroll
;             for (int j = 0; j < 4; ++j) cumt[j] = __shfl(cum, 16 * mb + 4 * fq + j);
; #pragma unroll
;             for (int i = 0; i < 2; ++i) { const int nb = 2 * hb + i; f32x4 sc = {0.f, 0.f, 0.f, 0.f};
; #pragma unroll
;                 for (int ks = 0; ks < 4; ++ks) sc = MFMA16(ca[ks], bbf[i][ks], sc);
;                 const int s = 16 * nb + fr; const float cums = __shfl(cum, s), dts = __shfl(dtv, s);
; #pragma unroll
;                 for (int j = 0; j < 4; ++j) { const int t = 16 * mb + 4 * fq + j; Pm[t * 72 + s] = f2bf(s <= t ? sc[j] * __expf(cumt[j] - cums) * dts : 0.f); } }
;             LDS_BARRIER();
	s_waitcnt vmcnt(2)
	v_mul_f32_e64 v78, v113, -v166
	ds_bpermute_b32 v79, v130, v78
	ds_write_b16 v159, v70 offset:63488
	ds_write_b16_d16_hi v159, v70 offset:63632
	ds_write_b16 v159, v71 offset:63776
	ds_write_b16_d16_hi v159, v71 offset:63920
	ds_write_b16 v159, v72 offset:64064
	ds_write_b16_d16_hi v159, v72 offset:64208
	ds_write_b16 v159, v73 offset:64352
	ds_write_b16_d16_hi v159, v73 offset:64496
	v_lshlrev_b32_e32 v71, 16, v74
	v_and_b32_e32 v72, 0xffff0000, v74
	v_add_u32_e32 v81, s3, v151
	s_waitcnt lgkmcnt(8)
	v_fma_f32 v79, v113, -v166, v79
	v_cndmask_b32_e64 v78, v79, v78, s[38:39]
	ds_bpermute_b32 v79, v131, v78
	v_lshlrev_b32_e32 v73, 16, v75
	v_and_b32_e32 v74, 0xffff0000, v75
	v_lshlrev_b32_e32 v75, 16, v76
	v_and_b32_e32 v76, 0xffff0000, v76
	s_waitcnt lgkmcnt(0)
	v_add_f32_e32 v79, v78, v79
	v_cndmask_b32_e64 v78, v79, v78, s[40:41]
	ds_bpermute_b32 v79, v132, v78
	v_mfma_f32_16x16x32_bf16 v[46:49], v[30:33], v[46:49], 0
	s_or_b32 s5, s5, 0x7c0
	s_waitcnt lgkmcnt(0)
	v_add_f32_e32 v79, v78, v79
	v_cndmask_b32_e64 v78, v79, v78, s[42:43]
	ds_bpermute_b32 v79, v133, v78
	v_mfma_f32_16x16x32_bf16 v[38:41], v[26:29], v[38:41], v[46:49]
	s_waitcnt lgkmcnt(0)
	v_add_f32_e32 v79, v78, v79
	v_cndmask_b32_e64 v78, v79, v78, s[44:45]
	ds_bpermute_b32 v79, v134, v78
	v_mfma_f32_16x16x32_bf16 v[54:57], v[30:33], v[54:57], 0
	s_waitcnt lgkmcnt(0)
	v_add_f32_e32 v79, v78, v79
	v_cndmask_b32_e64 v78, v79, v78, s[46:47]
	ds_bpermute_b32 v79, v135, v78
	v_mfma_f32_16x16x32_bf16 v[38:41], v[20:23], v[42:45], v[38:41]
	s_waitcnt lgkmcnt(0)
	v_add_f32_e32 v79, v78, v79
	v_cndmask_b32_e64 v79, v79, v78, s[48:49]
	ds_bpermute_b32 v78, v123, v79
	v_mfma_f32_16x16x32_bf16 v[54:57], v[26:29], v[58:61], v[54:57]
	ds_bpermute_b32 v58, v140, v79
	ds_bpermute_b32 v59, v140, v113
	s_waitcnt lgkmcnt(2)
	v_sub_f32_e32 v80, v78, v79
	v_mul_f32_e32 v80, 0x3fb8aa3b, v80
	v_exp_f32_e32 v80, v80
	v_mfma_f32_16x16x32_bf16 v[34:37], v[16:19], v[34:37], v[38:41]
	v_mul_f32_e32 v70, v113, v80
	v_mul_f32_e32 v71, v70, v71
	v_cvt_pk_bf16_f32 v71, v71, s0
	ds_write_b16 v81, v71
	v_mul_f32_e32 v71, v70, v72
	v_cvt_pk_bf16_f32 v71, v71, s0
	ds_write_b16 v81, v71 offset:144
	v_mul_f32_e32 v71, v70, v73
	v_cvt_pk_bf16_f32 v71, v71, s0
	ds_write_b16 v81, v71 offset:288
	v_mul_f32_e32 v71, v70, v74
	v_cvt_pk_bf16_f32 v71, v71, s0
	ds_write_b16 v81, v71 offset:432
	v_mul_f32_e32 v71, v70, v75
	v_cvt_pk_bf16_f32 v71, v71, s0
	ds_write_b16 v81, v71 offset:576
	v_mul_f32_e32 v71, v70, v76
	v_lshlrev_b32_e32 v80, 16, v77
	v_cvt_pk_bf16_f32 v71, v71, s0
	ds_write_b16 v81, v71 offset:720
	v_mul_f32_e32 v71, v70, v80
	v_and_b32_e32 v77, 0xffff0000, v77
	v_cvt_pk_bf16_f32 v71, v71, s0
	ds_write_b16 v81, v71 offset:864
	v_mul_f32_e32 v71, v70, v77
	v_cvt_pk_bf16_f32 v71, v71, s0
	ds_write_b16 v81, v71 offset:1008
	v_lshlrev_b32_e32 v71, 16, v50
	v_and_b32_e32 v50, 0xffff0000, v50
	v_mul_f32_e32 v50, v70, v50
	v_lshlrev_b32_e32 v72, 16, v51
	v_cvt_pk_bf16_f32 v50, v50, s0
	ds_write_b16 v81, v50 offset:9360
	v_mul_f32_e32 v50, v70, v72
	v_and_b32_e32 v51, 0xffff0000, v51
	v_cvt_pk_bf16_f32 v50, v50, s0
	ds_write_b16 v81, v50 offset:9504
	v_mul_f32_e32 v50, v70, v51
	v_lshlrev_b32_e32 v73, 16, v52
	v_cvt_pk_bf16_f32 v50, v50, s0
	ds_write_b16 v81, v50 offset:9648
	v_mul_f32_e32 v50, v70, v73
	v_and_b32_e32 v52, 0xffff0000, v52
	v_cvt_pk_bf16_f32 v50, v50, s0
	ds_write_b16 v81, v50 offset:9792
	v_mul_f32_e32 v50, v70, v52
	v_lshlrev_b32_e32 v74, 16, v53
	v_cvt_pk_bf16_f32 v50, v50, s0
	ds_write_b16 v81, v50 offset:9936
	v_mul_f32_e32 v50, v70, v74
	v_and_b32_e32 v53, 0xffff0000, v53
	v_cvt_pk_bf16_f32 v50, v50, s0
	ds_write_b16 v81, v50 offset:10080
	v_mul_f32_e32 v50, v70, v53
	ds_bpermute_b32 v53, v136, v79
	ds_bpermute_b32 v38, v145, v79
	v_mfma_f32_16x16x32_bf16 v[54:57], v[20:23], v[66:69], v[54:57]
	ds_bpermute_b32 v39, v145, v113
	ds_bpermute_b32 v52, v137, v79
	s_waitcnt lgkmcnt(3)
	v_sub_f32_e32 v60, v53, v58
	s_waitcnt lgkmcnt(2)
	v_sub_f32_e32 v40, v53, v38
	v_mul_f32_e32 v60, 0x3fb8aa3b, v60
	v_mul_f32_e32 v40, 0x3fb8aa3b, v40
	v_mfma_f32_16x16x32_bf16 v[54:57], v[16:19], v[62:65], v[54:57]
	v_exp_f32_e32 v60, v60
	v_exp_f32_e32 v40, v40
	v_mul_f32_e32 v71, v70, v71
	v_cvt_pk_bf16_f32 v71, v71, s0
	v_add_u32_e32 v75, s21, v151
	s_nop 2
	v_mul_f32_e32 v54, v54, v60
	v_mul_f32_e32 v34, v34, v40
	v_mul_f32_e32 v54, v54, v59
	s_waitcnt lgkmcnt(1)
	v_mul_f32_e32 v34, v34, v39
	v_cvt_pk_bf16_f32 v54, v54, s0
	v_cvt_pk_bf16_f32 v34, v34, s0
	v_cvt_pk_bf16_f32 v50, v50, s0
	v_cndmask_b32_e64 v54, v54, 0, s[50:51]
	v_cndmask_b32_e64 v34, v34, 0, s[58:59]
	ds_write_b16 v75, v71
	ds_write_b16 v81, v50 offset:10224
	ds_write_b16 v160, v54 offset:54272
	s_waitcnt lgkmcnt(3)
	v_sub_f32_e32 v54, v52, v58
	ds_write_b16 v160, v34 offset:54304
	v_sub_f32_e32 v34, v52, v38
	v_mul_f32_e32 v54, 0x3fb8aa3b, v54
	v_mul_f32_e32 v34, 0x3fb8aa3b, v34
	v_exp_f32_e32 v54, v54
	v_exp_f32_e32 v34, v34
	ds_bpermute_b32 v51, v138, v79
	ds_bpermute_b32 v50, v139, v79
	v_mul_f32_e32 v54, v55, v54
	v_mul_f32_e32 v34, v35, v34
	v_mul_f32_e32 v54, v54, v59
	v_mul_f32_e32 v34, v34, v39
	v_cvt_pk_bf16_f32 v54, v54, s0
	v_cvt_pk_bf16_f32 v34, v34, s0
	v_cndmask_b32_e64 v54, v54, 0, s[52:53]
	v_cndmask_b32_e64 v34, v34, 0, s[60:61]
	ds_write_b16 v160, v54 offset:54416
	s_waitcnt lgkmcnt(2)
	v_sub_f32_e32 v54, v51, v58
	ds_write_b16 v160, v34 offset:54448
	v_sub_f32_e32 v34, v51, v38
	v_mul_f32_e32 v54, 0x3fb8aa3b, v54
	v_mul_f32_e32 v34, 0x3fb8aa3b, v34
	v_exp_f32_e32 v54, v54
	v_exp_f32_e32 v34, v34
	v_add_u32_e32 v55, v128, v147
	v_mov_b32_e32 v113, v25
	v_mul_f32_e32 v54, v56, v54
	v_mul_f32_e32 v34, v36, v34
	v_mul_f32_e32 v54, v54, v59
	v_mul_f32_e32 v34, v34, v39
	v_cvt_pk_bf16_f32 v54, v54, s0
	v_cvt_pk_bf16_f32 v34, v34, s0
	v_cndmask_b32_e64 v54, v54, 0, s[54:55]
	v_cndmask_b32_e64 v34, v34, 0, s[62:63]
	ds_write_b16 v160, v54 offset:54560
	s_waitcnt lgkmcnt(3)
	v_sub_f32_e32 v54, v50, v58
	ds_write_b16 v160, v34 offset:54592
	v_sub_f32_e32 v34, v50, v38
	v_mul_f32_e32 v54, 0x3fb8aa3b, v54
	v_mul_f32_e32 v34, 0x3fb8aa3b, v34
	v_exp_f32_e32 v54, v54
	v_exp_f32_e32 v34, v34
	v_mul_f32_e32 v54, v57, v54
	v_mul_f32_e32 v34, v37, v34
	v_mul_f32_e32 v54, v54, v59
	v_mul_f32_e32 v34, v34, v39
	v_cvt_pk_bf16_f32 v54, v54, s0
	v_cvt_pk_bf16_f32 v34, v34, s0
	v_cndmask_b32_e64 v54, v54, 0, s[56:57]
	v_cndmask_b32_e64 v34, v34, 0, s[64:65]
	ds_write_b16 v160, v54 offset:54704
	ds_write_b16 v160, v34 offset:54736
	s_waitcnt lgkmcnt(0)
	s_barrier
; #define LAS __attribute__((address_space(3)))
; DI float bf2f(bf16_t b) { return __uint_as_float(((unsigned)b) << 16); }
; DI bf16_t f2bf(float f) { return (bf16_t)(pk2(f, 0.f) & 0xffffu); }
; #define MFMA16(a, b, c) __builtin_amdgcn_mfma_f32_16x16x32_bf16((a), (b), (c), 0, 0, 0)
; DI void ssd_scan(const Params& P, LAS unsigned char* lds) {
;     ...
;             f32x4 yi[2], ye[2];
; #pragma unroll
;             for (int i = 0; i < 2; ++i) { yi[i] = (f32x4){0.f, 0.f, 0.f, 0.f}; ye[i] = (f32x4){0.f, 0.f, 0.f, 0.f}; }
; #pragma unroll
;             for (int k2 = 0; k2 < 2; ++k2) { const bf16x8 am = *(const LAS bf16x8*)(Pm + (16 * mb + fr) * 72 + 32 * k2 + 8 * fq);
; #pragma unroll
;                 for (int i = 0; i < 2; ++i) { const bf16x8 bb = *(const LAS bf16x8*)(Xt + (16 * (2 * hb + i) + fr) * 72 + 32 * k2 + 8 * fq); yi[i] = MFMA16(am, bb, yi[i]); } }
; #pragma unroll
;             for (int ks = 0; ks < 4; ++ks)
; #pragma unroll
;                 for (int i = 0; i < 2; ++i) { const bf16x8 bb = *(const LAS bf16x8*)(Sb + (16 * (2 * hb + i) + fr) * 136 + 32 * ks + 8 * fq); ye[i] = MFMA16(ca[ks], bb, ye[i]); }
; #pragma unroll
;             for (int j = 0; j < 4; ++j) { const int tl = 16 * mb + 4 * fq + j, row = row0 + tl; const float ec = __expf(cumt[j]);
; #pragma unroll
;                 for (int i = 0; i < 2; ++i) { const int p = 16 * (2 * hb + i) + fr; const float xv = bf2f(Xt[p * 72 + tl]);
;                     YB[(size_t)row * 2048 + h * 64 + p] = f2bf(yi[i][j] + ec * ye[i][j] + dsk * xv); } }
;             { const float ecl = __expf(cl);
; #pragma unroll
;               for (int i = 0; i < 4; ++i) Sacc[i] *= ecl; }
	ds_read_b128 v[34:37], v129 offset:54272
	v_add_u32_e32 v54, v128, v146
	ds_read_b128 v[38:41], v54 offset:63488
	ds_read_b128 v[42:45], v55 offset:63488
	s_waitcnt lgkmcnt(1)
	v_mfma_f32_16x16x32_bf16 v[38:41], v[34:37], v[38:41], 0
	s_waitcnt lgkmcnt(0)
	v_mfma_f32_16x16x32_bf16 v[42:45], v[34:37], v[42:45], 0
	ds_read_b128 v[46:49], v129 offset:54336
	ds_read_b128 v[34:37], v54 offset:63552
	s_waitcnt lgkmcnt(0)
	v_mfma_f32_16x16x32_bf16 v[34:37], v[46:49], v[34:37], v[38:41]
	s_nop 2
	ds_read_b128 v[38:41], v55 offset:63552
	s_waitcnt lgkmcnt(0)
	v_mfma_f32_16x16x32_bf16 v[38:41], v[46:49], v[38:41], v[42:45]
	s_nop 2
	ds_read_b128 v[42:45], v161
	ds_read_b128 v[46:49], v161 offset:4352
	s_waitcnt lgkmcnt(1)
	v_mfma_f32_16x16x32_bf16 v[42:45], v[30:33], v[42:45], 0
	s_waitcnt lgkmcnt(0)
	v_mfma_f32_16x16x32_bf16 v[30:33], v[30:33], v[46:49], 0
	ds_read_b128 v[46:49], v161 offset:64
	s_waitcnt lgkmcnt(0)
	v_mfma_f32_16x16x32_bf16 v[42:45], v[26:29], v[46:49], v[42:45]
	ds_read_b128 v[46:49], v161 offset:4416
	s_waitcnt lgkmcnt(0)
	v_mfma_f32_16x16x32_bf16 v[26:29], v[26:29], v[46:49], v[30:33]
	s_nop 2
	ds_read_b128 v[30:33], v161 offset:128
	s_waitcnt lgkmcnt(0)
	v_mfma_f32_16x16x32_bf16 v[30:33], v[20:23], v[30:33], v[42:45]
	s_nop 2
	ds_read_b128 v[42:45], v161 offset:4480
	s_waitcnt lgkmcnt(0)
	v_mfma_f32_16x16x32_bf16 v[20:23], v[20:23], v[42:45], v[26:29]
	s_nop 2
	ds_read_b128 v[26:29], v161 offset:192
	s_waitcnt lgkmcnt(0)
	v_mfma_f32_16x16x32_bf16 v[26:29], v[16:19], v[26:29], v[30:33]
	s_nop 2
	ds_read_b128 v[30:33], v161 offset:4544
	s_waitcnt lgkmcnt(0)
	v_mfma_f32_16x16x32_bf16 v[16:19], v[16:19], v[30:33], v[20:23]
	s_nop 2
	v_add_u32_e32 v22, v152, v146
	v_mul_f32_e32 v21, 0x3fb8aa3b, v53
	ds_read_b64 v[22:23], v22 offset:63488
	v_exp_f32_e32 v32, v21
	v_add_u32_e32 v20, s5, v124
	v_ashrrev_i32_e32 v21, 31, v20
	v_lshlrev_b64 v[20:21], 12, v[20:21]
	s_waitcnt lgkmcnt(0)
	v_lshlrev_b32_e32 v30, 16, v22
	v_fma_f32 v26, v32, v26, v34
	v_fmac_f32_e32 v26, v111, v30
	v_lshl_add_u64 v[20:21], v[104:105], 0, v[20:21]
	v_cvt_pk_bf16_f32 v26, v26, s0
	v_lshl_add_u64 v[20:21], v[20:21], 0, s[36:37]
	global_store_short v[20:21], v26, off
	v_add_u32_e32 v26, v152, v147
	ds_read_b64 v[30:31], v26 offset:63488
	v_fma_f32 v16, v32, v16, v38
	v_and_b32_e32 v22, 0xffff0000, v22
	s_waitcnt lgkmcnt(0)
	v_lshlrev_b32_e32 v26, 16, v30
	v_fmac_f32_e32 v16, v111, v26
	v_cvt_pk_bf16_f32 v16, v16, s0
	global_store_short v[20:21], v16, off offset:32
	v_mul_f32_e32 v16, 0x3fb8aa3b, v52
	v_exp_f32_e32 v16, v16
	v_add_u32_e32 v20, s5, v142
	v_ashrrev_i32_e32 v21, 31, v20
	v_lshlrev_b64 v[20:21], 12, v[20:21]
	v_fma_f32 v26, v16, v27, v35
	v_fmac_f32_e32 v26, v111, v22
	v_lshl_add_u64 v[20:21], v[104:105], 0, v[20:21]
	v_cvt_pk_bf16_f32 v22, v26, s0
	v_lshl_add_u64 v[20:21], v[20:21], 0, s[36:37]
	global_store_short v[20:21], v22, off
	v_and_b32_e32 v22, 0xffff0000, v30
	v_fma_f32 v16, v16, v17, v39
	v_fmac_f32_e32 v16, v111, v22
	v_cvt_pk_bf16_f32 v16, v16, s0
	v_mul_f32_e32 v17, 0x3fb8aa3b, v51
	global_store_short v[20:21], v16, off offset:32
	v_exp_f32_e32 v20, v17
	v_add_u32_e32 v16, s5, v143
	v_ashrrev_i32_e32 v17, 31, v16
	v_lshlrev_b32_e32 v21, 16, v23
	v_fma_f32 v22, v20, v28, v36
	v_lshlrev_b64 v[16:17], 12, v[16:17]
	v_fmac_f32_e32 v22, v111, v21
	v_lshl_add_u64 v[16:17], v[104:105], 0, v[16:17]
	v_cvt_pk_bf16_f32 v21, v22, s0
	v_lshl_add_u64 v[16:17], v[16:17], 0, s[36:37]
	global_store_short v[16:17], v21, off
	v_lshlrev_b32_e32 v21, 16, v31
	v_fma_f32 v18, v20, v18, v40
	v_fmac_f32_e32 v18, v111, v21
	v_cvt_pk_bf16_f32 v18, v18, s0
	global_store_short v[16:17], v18, off offset:32
	v_mul_f32_e32 v17, 0x3fb8aa3b, v50
	v_exp_f32_e32 v18, v17
	v_add_u32_e32 v16, s5, v144
	v_ashrrev_i32_e32 v17, 31, v16
	v_and_b32_e32 v20, 0xffff0000, v23
	v_fmac_f32_e32 v37, v18, v29
	v_lshlrev_b64 v[16:17], 12, v[16:17]
	v_fmac_f32_e32 v37, v111, v20
	v_lshl_add_u64 v[16:17], v[104:105], 0, v[16:17]
	v_cvt_pk_bf16_f32 v20, v37, s0
	v_lshl_add_u64 v[16:17], v[16:17], 0, s[36:37]
	global_store_short v[16:17], v20, off
	v_and_b32_e32 v20, 0xffff0000, v31
	v_fmac_f32_e32 v41, v18, v19
	v_fmac_f32_e32 v41, v111, v20
	v_cvt_pk_bf16_f32 v18, v41, s0
	global_store_short v[16:17], v18, off offset:32
	v_mul_f32_e32 v16, 0x3fb8aa3b, v78
	v_exp_f32_e32 v16, v16
	v_add_u32_e32 v26, v128, v149
	ds_read_b128 v[20:23], v26 offset:63488
	s_ashr_i32 s5, s4, 31
	v_pk_mul_f32 v[2:3], v[2:3], v[16:17] op_sel_hi:[1,0]
	v_pk_mul_f32 v[0:1], v[0:1], v[16:17] op_sel_hi:[1,0]
	v_pk_mul_f32 v[6:7], v[6:7], v[16:17] op_sel_hi:[1,0]
	v_pk_mul_f32 v[4:5], v[4:5], v[16:17] op_sel_hi:[1,0]
	v_pk_mul_f32 v[14:15], v[14:15], v[16:17] op_sel_hi:[1,0]
	v_pk_mul_f32 v[12:13], v[12:13], v[16:17] op_sel_hi:[1,0]
	v_pk_mul_f32 v[10:11], v[10:11], v[16:17] op_sel_hi:[1,0]
	v_pk_mul_f32 v[8:9], v[8:9], v[16:17] op_sel_hi:[1,0]
	ds_read_b128 v[16:19], v153
	s_waitcnt lgkmcnt(0)
; #define LAS __attribute__((address_space(3)))
; DI unsigned pk2(float lo, float hi) { const f32x2v v = {lo, hi}; const bf16x2v b = __builtin_convertvector(v, bf16x2v); return __builtin_bit_cast(unsigned, b); }
; #define LDS_BARRIER() do { asm volatile("s_waitcnt lgkmcnt(0)" ::: "memory"); __builtin_amdgcn_s_barrier(); asm volatile("" ::: "memory"); } while (0)
; #define MFMA16(a, b, c) __builtin_amdgcn_mfma_f32_16x16x32_bf16((a), (b), (c), 0, 0, 0)
; DI void ssd_scan(const Params& P, LAS unsigned char* lds) {
;     ...
; #pragma unroll
;             for (int k2 = 0; k2 < 2; ++k2) { const bf16x8 am = *(const LAS bf16x8*)(BWt + (16 * wid + fr) * 72 + 32 * k2 + 8 * fq);
; #pragma unroll
;                 for (int i = 0; i < 4; ++i) { const bf16x8 bb = *(const LAS bf16x8*)(Xt + (16 * i + fr) * 72 + 32 * k2 + 8 * fq); Sacc[i] = MFMA16(am, bb, Sacc[i]); } }
; #pragma unroll
;             for (int i = 0; i < 4; ++i) { u32x2 w; w.x = pk2(Sacc[i][0], Sacc[i][1]); w.y = pk2(Sacc[i][2], Sacc[i][3]); *(LAS u32x2*)(Sbn + (16 * i + fr) * 136 + 16 * wid + 4 * fq) = w; }
;             dtv = dtn;
; #pragma unroll
;             for (int ks = 0; ks < 4; ++ks) ca[ks] = cn[ks];
;         }
;     ...
;         float* SO = P.out + OUT_SSMP + ((size_t)(b * 32 + h) * 64) * 128;
; #pragma unroll
;         for (int i = 0; i < 4; ++i) *(f32x4*)(SO + (size_t)(16 * i + fr) * 128 + 16 * wid + 4 * fq) = Sacc[i];
;         LDS_BARRIER();
	v_mfma_f32_16x16x32_bf16 v[0:3], v[16:19], v[20:23], v[0:3]
	ds_read_b128 v[20:23], v162 offset:63488
	s_lshl_b64 s[16:17], s[4:5], 15
	v_mov_b32_e32 v111, v25
	s_waitcnt lgkmcnt(0)
	v_mfma_f32_16x16x32_bf16 v[4:7], v[16:19], v[20:23], v[4:7]
	ds_read_b128 v[20:23], v163 offset:63488
	s_waitcnt lgkmcnt(0)
	v_mfma_f32_16x16x32_bf16 v[12:15], v[16:19], v[20:23], v[12:15]
	ds_read_b128 v[20:23], v164 offset:63488
	s_waitcnt lgkmcnt(0)
	v_mfma_f32_16x16x32_bf16 v[8:11], v[16:19], v[20:23], v[8:11]
	ds_read_b128 v[16:19], v153 offset:64
	ds_read_b128 v[20:23], v26 offset:63552
	s_load_dwordx2 s[14:15], s[0:1], 0x150
	s_waitcnt lgkmcnt(0)
	s_add_u32 s5, s14, s16
	v_mfma_f32_16x16x32_bf16 v[0:3], v[16:19], v[20:23], v[0:3]
	ds_read_b128 v[20:23], v162 offset:63552
	s_addc_u32 s13, s15, s17
	s_add_u32 s14, s5, s22
	s_waitcnt lgkmcnt(0)
	v_mfma_f32_16x16x32_bf16 v[4:7], v[16:19], v[20:23], v[4:7]
	ds_read_b128 v[20:23], v163 offset:63552
	s_addc_u32 s15, s13, 0
	s_mov_b32 s5, 0x8ff8000
	s_waitcnt lgkmcnt(0)
	v_mfma_f32_16x16x32_bf16 v[12:15], v[16:19], v[20:23], v[12:15]
	ds_read_b128 v[20:23], v164 offset:63552
	s_waitcnt lgkmcnt(0)
	v_mfma_f32_16x16x32_bf16 v[8:11], v[16:19], v[20:23], v[8:11]
	v_cvt_pk_bf16_f32 v16, v0, v1
	v_cvt_pk_bf16_f32 v17, v2, v3
	v_add_u32_e32 v18, v154, v150
	ds_write_b64 v18, v[16:17] offset:18432
	v_cvt_pk_bf16_f32 v16, v4, v5
	v_cvt_pk_bf16_f32 v17, v6, v7
	ds_write_b64 v18, v[16:17] offset:22784
	v_cvt_pk_bf16_f32 v16, v12, v13
	v_cvt_pk_bf16_f32 v17, v14, v15
	ds_write_b64 v18, v[16:17] offset:27136
	v_cvt_pk_bf16_f32 v16, v8, v9
	v_cvt_pk_bf16_f32 v17, v10, v11
	ds_write_b64 v18, v[16:17] offset:31488
	v_lshl_add_u64 v[16:17], s[14:15], 0, v[110:111]
	v_lshl_add_u64 v[16:17], v[16:17], 0, v[112:113]
	v_add_co_u32_e32 v18, vcc, s5, v16
	s_mov_b32 s5, 0x8ffa000
	s_nop 0
	v_addc_co_u32_e32 v19, vcc, 0, v17, vcc
	global_store_dwordx4 v[18:19], v[0:3], off
	v_readlane_b32 s14, v255, 13
	v_readlane_b32 s15, v255, 14
	v_add_co_u32_e32 v0, vcc, s5, v16
	s_mov_b32 s5, 0x8ffc000
	s_nop 0
	v_addc_co_u32_e32 v1, vcc, 0, v17, vcc
	global_store_dwordx4 v[0:1], v[4:7], off
	v_add_co_u32_e32 v0, vcc, s5, v16
	s_nop 1
	v_addc_co_u32_e32 v1, vcc, 0, v17, vcc
	global_store_dwordx4 v[0:1], v[12:15], off
	v_add_co_u32_e32 v0, vcc, 0x8ffe000, v16
	s_nop 1
	v_addc_co_u32_e32 v1, vcc, 0, v17, vcc
	global_store_dwordx4 v[0:1], v[8:11], off
	s_waitcnt lgkmcnt(0)
	s_barrier
	s_load_dword s5, s[14:15], 0x0
	s_waitcnt lgkmcnt(0)
	s_add_i32 s4, s5, s4
	s_cmpk_gt_i32 s4, 0xff
	s_cbranch_scc0 .LBB0_174
